# phase 1 rmsnorm: all 8 rows of a wave loaded up front (512-workgroup fast path)
# baseline (speedup 1.0000x reference)
.LBB0_284:
	s_or_b64 exec, exec, s[6:7]
	s_and_b64 s[2:3], s[2:3], exec
	v_readlane_b32 s4, v251, 8
	v_readlane_b32 s2, v254, 30
	v_readlane_b32 s5, v251, 9
	v_readlane_b32 s3, v254, 31
	s_cselect_b32 s47, s5, s87
	s_cselect_b32 s46, s4, s86
	s_lshl_b32 s2, s2, 10
	s_mov_b32 s3, s77
	v_writelane_b32 v254, s2, 34
	v_mov_b32_e32 v0, v186
	v_readlane_b32 s6, v251, 10
	v_writelane_b32 v254, s3, 35
	v_ashrrev_i32_e32 v1, 6, v0
	v_readlane_b32 s2, v251, 47
	v_readlane_b32 s7, v251, 11
	v_readlane_b32 s8, v251, 12
	v_add_u32_e32 v16, s2, v1
	s_movk_i32 s2, 0x4000
	v_cmp_gt_i32_e32 vcc, s2, v16
	v_readlane_b32 s9, v251, 13
	v_readlane_b32 s10, v251, 14
	v_readlane_b32 s11, v251, 15
	v_readlane_b32 s12, v251, 16
	v_readlane_b32 s13, v251, 17
	v_readlane_b32 s14, v251, 18
	v_readlane_b32 s15, v251, 19
	v_readlane_b32 s16, v251, 20
	v_readlane_b32 s17, v251, 21
	v_readlane_b32 s18, v251, 22
	v_readlane_b32 s19, v251, 23
	s_and_saveexec_b64 s[2:3], vcc
	v_readlane_b32 s6, v254, 23
	v_readlane_b32 s7, v254, 24
	s_cbranch_execz .LBB0_287
	v_readlane_b32 s4, v254, 34
	v_readlane_b32 s5, v254, 35
	v_readlane_b32 s8, v251, 8
	s_lshl_b64 s[4:5], s[4:5], 2
	v_readlane_b32 s14, v251, 14
	v_lshlrev_b32_e32 v0, 2, v0
	v_readlane_b32 s15, v251, 15
	s_add_u32 s4, s14, s4
	v_and_b32_e32 v17, 0xfc, v0
	s_addc_u32 s5, s15, s5
	v_lshlrev_b32_e32 v160, 2, v17
	global_load_dwordx4 v[0:3], v160, s[4:5]
	global_load_dwordx4 v[4:7], v160, s[4:5] offset:1024
	global_load_dwordx4 v[8:11], v160, s[4:5] offset:2048
	global_load_dwordx4 v[12:15], v160, s[4:5] offset:3072
	v_and_b32_e32 v20, 64, v194
	v_add_u32_e32 v20, 64, v20
	v_xor_b32_e32 v21, 32, v194
	v_cmp_lt_i32_e32 vcc, v21, v20
	v_lshl_add_u64 v[18:19], s[46:47], 0, v[160:161]
	v_readlane_b32 s9, v251, 9
	v_cndmask_b32_e32 v21, v194, v21, vcc
	v_lshlrev_b32_e32 v22, 2, v21
	v_xor_b32_e32 v21, 16, v194
	v_cmp_lt_i32_e32 vcc, v21, v20
	v_readlane_b32 s10, v251, 10
	v_readlane_b32 s11, v251, 11
	v_cndmask_b32_e32 v21, v194, v21, vcc
	v_lshlrev_b32_e32 v23, 2, v21
	v_xor_b32_e32 v21, 8, v194
	v_cmp_lt_i32_e32 vcc, v21, v20
	v_readlane_b32 s12, v251, 12
	v_readlane_b32 s13, v251, 13
	v_cndmask_b32_e32 v21, v194, v21, vcc
	v_lshlrev_b32_e32 v24, 2, v21
	v_xor_b32_e32 v21, 4, v194
	v_cmp_lt_i32_e32 vcc, v21, v20
	v_readlane_b32 s16, v251, 16
	v_readlane_b32 s17, v251, 17
	v_cndmask_b32_e32 v21, v194, v21, vcc
	v_lshlrev_b32_e32 v25, 2, v21
	v_xor_b32_e32 v21, 2, v194
	v_cmp_lt_i32_e32 vcc, v21, v20
	v_readlane_b32 s18, v251, 18
	v_readlane_b32 s19, v251, 19
	v_cndmask_b32_e32 v21, v194, v21, vcc
	v_lshlrev_b32_e32 v26, 2, v21
	v_xor_b32_e32 v21, 1, v194
	v_cmp_lt_i32_e32 vcc, v21, v20
	v_readlane_b32 s20, v251, 20
	v_readlane_b32 s21, v251, 21
	v_cndmask_b32_e32 v20, v194, v21, vcc
	v_lshlrev_b32_e32 v27, 2, v20
	v_lshlrev_b32_e32 v20, 1, v17
	v_mov_b32_e32 v21, v161
	v_lshl_add_u64 v[20:21], s[0:1], 0, v[20:21]
	s_mov_b64 s[0:1], 0x2800000
	v_lshl_add_u64 v[20:21], v[20:21], 0, s[0:1]
	s_mov_b64 s[0:1], 0
	v_readlane_b32 s22, v251, 22
	v_readlane_b32 s23, v251, 23
	s_cmpk_lg_i32 s90, 0x200
	s_cbranch_scc1 .LBB0_286
	v_ashrrev_i32_e32 v17, 31, v16
	v_lshlrev_b64 v[28:29], 12, v[16:17]
	v_lshl_add_u64 v[40:41], v[18:19], 0, v[28:29]
	v_lshlrev_b64 v[28:29], 11, v[16:17]
	v_lshl_add_u64 v[44:45], v[20:21], 0, v[28:29]
	global_load_dwordx4 v[28:31], v[40:41], off
	global_load_dwordx4 v[32:35], v[40:41], off offset:1024
	global_load_dwordx4 v[56:59], v[40:41], off offset:2048
	global_load_dwordx4 v[60:63], v[40:41], off offset:3072
	v_add_u32_e32 v16, s6, v16
	v_ashrrev_i32_e32 v17, 31, v16
	v_lshlrev_b64 v[84:85], 12, v[16:17]
	v_lshl_add_u64 v[40:41], v[18:19], 0, v[84:85]
	v_lshlrev_b64 v[84:85], 11, v[16:17]
	v_lshl_add_u64 v[64:65], v[20:21], 0, v[84:85]
	global_load_dwordx4 v[84:87], v[40:41], off
	global_load_dwordx4 v[88:91], v[40:41], off offset:1024
	global_load_dwordx4 v[92:95], v[40:41], off offset:2048
	global_load_dwordx4 v[96:99], v[40:41], off offset:3072
	v_add_u32_e32 v16, s6, v16
	v_ashrrev_i32_e32 v17, 31, v16
	v_lshlrev_b64 v[100:101], 12, v[16:17]
	v_lshl_add_u64 v[40:41], v[18:19], 0, v[100:101]
	v_lshlrev_b64 v[100:101], 11, v[16:17]
	v_lshl_add_u64 v[66:67], v[20:21], 0, v[100:101]
	global_load_dwordx4 v[100:103], v[40:41], off
	global_load_dwordx4 v[104:107], v[40:41], off offset:1024
	global_load_dwordx4 v[108:111], v[40:41], off offset:2048
	global_load_dwordx4 v[112:115], v[40:41], off offset:3072
	v_add_u32_e32 v16, s6, v16
	v_ashrrev_i32_e32 v17, 31, v16
	v_lshlrev_b64 v[116:117], 12, v[16:17]
	v_lshl_add_u64 v[40:41], v[18:19], 0, v[116:117]
	v_lshlrev_b64 v[116:117], 11, v[16:17]
	v_lshl_add_u64 v[68:69], v[20:21], 0, v[116:117]
	global_load_dwordx4 v[116:119], v[40:41], off
	global_load_dwordx4 v[120:123], v[40:41], off offset:1024
	global_load_dwordx4 v[124:127], v[40:41], off offset:2048
	global_load_dwordx4 v[128:131], v[40:41], off offset:3072
	v_add_u32_e32 v16, s6, v16
	v_ashrrev_i32_e32 v17, 31, v16
	v_lshlrev_b64 v[132:133], 12, v[16:17]
	v_lshl_add_u64 v[40:41], v[18:19], 0, v[132:133]
	v_lshlrev_b64 v[132:133], 11, v[16:17]
	v_lshl_add_u64 v[70:71], v[20:21], 0, v[132:133]
	global_load_dwordx4 v[132:135], v[40:41], off
	global_load_dwordx4 v[136:139], v[40:41], off offset:1024
	global_load_dwordx4 v[140:143], v[40:41], off offset:2048
	global_load_dwordx4 v[144:147], v[40:41], off offset:3072
	v_add_u32_e32 v16, s6, v16
	v_ashrrev_i32_e32 v17, 31, v16
	v_lshlrev_b64 v[164:165], 12, v[16:17]
	v_lshl_add_u64 v[40:41], v[18:19], 0, v[164:165]
	v_lshlrev_b64 v[164:165], 11, v[16:17]
	v_lshl_add_u64 v[72:73], v[20:21], 0, v[164:165]
	global_load_dwordx4 v[164:167], v[40:41], off
	global_load_dwordx4 v[168:171], v[40:41], off offset:1024
	global_load_dwordx4 v[172:175], v[40:41], off offset:2048
	global_load_dwordx4 v[176:179], v[40:41], off offset:3072
	v_add_u32_e32 v16, s6, v16
	v_ashrrev_i32_e32 v17, 31, v16
	v_lshlrev_b64 v[210:211], 12, v[16:17]
	v_lshl_add_u64 v[40:41], v[18:19], 0, v[210:211]
	v_lshlrev_b64 v[210:211], 11, v[16:17]
	v_lshl_add_u64 v[74:75], v[20:21], 0, v[210:211]
	global_load_dwordx4 v[210:213], v[40:41], off
	global_load_dwordx4 v[214:217], v[40:41], off offset:1024
	global_load_dwordx4 v[218:221], v[40:41], off offset:2048
	global_load_dwordx4 v[222:225], v[40:41], off offset:3072
	v_add_u32_e32 v16, s6, v16
	v_ashrrev_i32_e32 v17, 31, v16
	v_lshlrev_b64 v[226:227], 12, v[16:17]
	v_lshl_add_u64 v[40:41], v[18:19], 0, v[226:227]
	v_lshlrev_b64 v[226:227], 11, v[16:17]
	v_lshl_add_u64 v[76:77], v[20:21], 0, v[226:227]
	global_load_dwordx4 v[226:229], v[40:41], off
	global_load_dwordx4 v[230:233], v[40:41], off offset:1024
	global_load_dwordx4 v[234:237], v[40:41], off offset:2048
	global_load_dwordx4 v[238:241], v[40:41], off offset:3072
	v_add_u32_e32 v16, s6, v16
	s_waitcnt vmcnt(31)
	v_mov_b32_e32 v46, v29
	s_waitcnt vmcnt(30)
	v_mov_b32_e32 v47, v33
	v_mov_b32_e32 v42, v28
	v_mov_b32_e32 v43, v32
	v_pk_mul_f32 v[46:47], v[46:47], v[46:47]
	v_mov_b32_e32 v36, v30
	v_mov_b32_e32 v37, v34
	v_pk_fma_f32 v[42:43], v[42:43], v[42:43], v[46:47]
	v_mov_b32_e32 v38, v31
	v_mov_b32_e32 v39, v35
	v_pk_fma_f32 v[36:37], v[36:37], v[36:37], v[42:43]
	s_nop 0
	v_pk_fma_f32 v[46:47], v[38:39], v[38:39], v[36:37]
	v_add_f32_e32 v17, v46, v47
	s_waitcnt vmcnt(29)
	v_mov_b32_e32 v54, v57
	s_waitcnt vmcnt(28)
	v_mov_b32_e32 v55, v61
	v_mov_b32_e32 v52, v56
	v_mov_b32_e32 v53, v60
	v_pk_mul_f32 v[54:55], v[54:55], v[54:55]
	v_mov_b32_e32 v48, v58
	v_mov_b32_e32 v49, v62
	v_pk_fma_f32 v[52:53], v[52:53], v[52:53], v[54:55]
	v_mov_b32_e32 v50, v59
	v_mov_b32_e32 v51, v63
	v_pk_fma_f32 v[48:49], v[48:49], v[48:49], v[52:53]
	s_nop 0
	v_pk_fma_f32 v[48:49], v[50:51], v[50:51], v[48:49]
	s_nop 0
	v_add_f32_e32 v17, v17, v48
	v_add_f32_e32 v17, v17, v49
	ds_bpermute_b32 v46, v22, v17
	s_waitcnt lgkmcnt(0)
	v_add_f32_e32 v17, v17, v46
	ds_bpermute_b32 v46, v23, v17
	s_waitcnt lgkmcnt(0)
	v_add_f32_e32 v17, v17, v46
	ds_bpermute_b32 v46, v24, v17
	s_waitcnt lgkmcnt(0)
	v_add_f32_e32 v17, v17, v46
	ds_bpermute_b32 v46, v25, v17
	s_waitcnt lgkmcnt(0)
	v_add_f32_e32 v17, v17, v46
	ds_bpermute_b32 v46, v26, v17
	s_waitcnt lgkmcnt(0)
	v_add_f32_e32 v17, v17, v46
	ds_bpermute_b32 v46, v27, v17
	s_waitcnt lgkmcnt(0)
	v_add_f32_e32 v17, v17, v46
	v_fmamk_f32 v17, v17, 0x3a800000, v187
	v_cmp_gt_f32_e32 vcc, s79, v17
	v_mul_f32_e32 v46, 0x4b800000, v17
	s_nop 0
	v_cndmask_b32_e32 v17, v17, v46, vcc
	v_rsq_f32_e32 v17, v17
	s_nop 0
	v_mul_f32_e32 v46, 0x45800000, v17
	v_cndmask_b32_e32 v46, v17, v46, vcc
	v_pk_mul_f32 v[28:29], v[28:29], v[46:47] op_sel_hi:[1,0]
	v_pk_mul_f32 v[30:31], v[30:31], v[46:47] op_sel_hi:[1,0]
	v_pk_mul_f32 v[28:29], v[0:1], v[28:29]
	v_pk_mul_f32 v[30:31], v[2:3], v[30:31]
	v_cvt_pk_bf16_f32 v28, v28, v29
	v_cvt_pk_bf16_f32 v29, v30, v31
	global_store_dwordx2 v[44:45], v[28:29], off
	v_pk_mul_f32 v[28:29], v[32:33], v[46:47] op_sel_hi:[1,0]
	v_pk_mul_f32 v[30:31], v[34:35], v[46:47] op_sel_hi:[1,0]
	v_pk_mul_f32 v[28:29], v[4:5], v[28:29]
	v_pk_mul_f32 v[30:31], v[6:7], v[30:31]
	v_cvt_pk_bf16_f32 v28, v28, v29
	v_cvt_pk_bf16_f32 v29, v30, v31
	global_store_dwordx2 v[44:45], v[28:29], off offset:512
	v_pk_mul_f32 v[28:29], v[56:57], v[46:47] op_sel_hi:[1,0]
	v_pk_mul_f32 v[30:31], v[58:59], v[46:47] op_sel_hi:[1,0]
	v_pk_mul_f32 v[28:29], v[8:9], v[28:29]
	v_pk_mul_f32 v[30:31], v[10:11], v[30:31]
	v_cvt_pk_bf16_f32 v28, v28, v29
	v_cvt_pk_bf16_f32 v29, v30, v31
	global_store_dwordx2 v[44:45], v[28:29], off offset:1024
	v_pk_mul_f32 v[28:29], v[60:61], v[46:47] op_sel_hi:[1,0]
	v_pk_mul_f32 v[30:31], v[62:63], v[46:47] op_sel_hi:[1,0]
	v_pk_mul_f32 v[28:29], v[12:13], v[28:29]
	v_pk_mul_f32 v[30:31], v[14:15], v[30:31]
	v_cvt_pk_bf16_f32 v28, v28, v29
	v_cvt_pk_bf16_f32 v29, v30, v31
	global_store_dwordx2 v[44:45], v[28:29], off offset:1536
	s_waitcnt vmcnt(31)
	v_mov_b32_e32 v46, v85
	s_waitcnt vmcnt(30)
	v_mov_b32_e32 v47, v89
	v_mov_b32_e32 v42, v84
	v_mov_b32_e32 v43, v88
	v_pk_mul_f32 v[46:47], v[46:47], v[46:47]
	v_mov_b32_e32 v36, v86
	v_mov_b32_e32 v37, v90
	v_pk_fma_f32 v[42:43], v[42:43], v[42:43], v[46:47]
	v_mov_b32_e32 v38, v87
	v_mov_b32_e32 v39, v91
	v_pk_fma_f32 v[36:37], v[36:37], v[36:37], v[42:43]
	s_nop 0
	v_pk_fma_f32 v[46:47], v[38:39], v[38:39], v[36:37]
	v_add_f32_e32 v17, v46, v47
	s_waitcnt vmcnt(29)
	v_mov_b32_e32 v54, v93
	s_waitcnt vmcnt(28)
	v_mov_b32_e32 v55, v97
	v_mov_b32_e32 v52, v92
	v_mov_b32_e32 v53, v96
	v_pk_mul_f32 v[54:55], v[54:55], v[54:55]
	v_mov_b32_e32 v48, v94
	v_mov_b32_e32 v49, v98
	v_pk_fma_f32 v[52:53], v[52:53], v[52:53], v[54:55]
	v_mov_b32_e32 v50, v95
	v_mov_b32_e32 v51, v99
	v_pk_fma_f32 v[48:49], v[48:49], v[48:49], v[52:53]
	s_nop 0
	v_pk_fma_f32 v[48:49], v[50:51], v[50:51], v[48:49]
	s_nop 0
	v_add_f32_e32 v17, v17, v48
	v_add_f32_e32 v17, v17, v49
	ds_bpermute_b32 v46, v22, v17
	s_waitcnt lgkmcnt(0)
	v_add_f32_e32 v17, v17, v46
	ds_bpermute_b32 v46, v23, v17
	s_waitcnt lgkmcnt(0)
	v_add_f32_e32 v17, v17, v46
	ds_bpermute_b32 v46, v24, v17
	s_waitcnt lgkmcnt(0)
	v_add_f32_e32 v17, v17, v46
	ds_bpermute_b32 v46, v25, v17
	s_waitcnt lgkmcnt(0)
	v_add_f32_e32 v17, v17, v46
	ds_bpermute_b32 v46, v26, v17
	s_waitcnt lgkmcnt(0)
	v_add_f32_e32 v17, v17, v46
	ds_bpermute_b32 v46, v27, v17
	s_waitcnt lgkmcnt(0)
	v_add_f32_e32 v17, v17, v46
	v_fmamk_f32 v17, v17, 0x3a800000, v187
	v_cmp_gt_f32_e32 vcc, s79, v17
	v_mul_f32_e32 v46, 0x4b800000, v17
	s_nop 0
	v_cndmask_b32_e32 v17, v17, v46, vcc
	v_rsq_f32_e32 v17, v17
	s_nop 0
	v_mul_f32_e32 v46, 0x45800000, v17
	v_cndmask_b32_e32 v46, v17, v46, vcc
	v_pk_mul_f32 v[84:85], v[84:85], v[46:47] op_sel_hi:[1,0]
	v_pk_mul_f32 v[86:87], v[86:87], v[46:47] op_sel_hi:[1,0]
	v_pk_mul_f32 v[84:85], v[0:1], v[84:85]
	v_pk_mul_f32 v[86:87], v[2:3], v[86:87]
	v_cvt_pk_bf16_f32 v84, v84, v85
	v_cvt_pk_bf16_f32 v85, v86, v87
	global_store_dwordx2 v[64:65], v[84:85], off
	v_pk_mul_f32 v[84:85], v[88:89], v[46:47] op_sel_hi:[1,0]
	v_pk_mul_f32 v[86:87], v[90:91], v[46:47] op_sel_hi:[1,0]
	v_pk_mul_f32 v[84:85], v[4:5], v[84:85]
	v_pk_mul_f32 v[86:87], v[6:7], v[86:87]
	v_cvt_pk_bf16_f32 v84, v84, v85
	v_cvt_pk_bf16_f32 v85, v86, v87
	global_store_dwordx2 v[64:65], v[84:85], off offset:512
	v_pk_mul_f32 v[84:85], v[92:93], v[46:47] op_sel_hi:[1,0]
	v_pk_mul_f32 v[86:87], v[94:95], v[46:47] op_sel_hi:[1,0]
	v_pk_mul_f32 v[84:85], v[8:9], v[84:85]
	v_pk_mul_f32 v[86:87], v[10:11], v[86:87]
	v_cvt_pk_bf16_f32 v84, v84, v85
	v_cvt_pk_bf16_f32 v85, v86, v87
	global_store_dwordx2 v[64:65], v[84:85], off offset:1024
	v_pk_mul_f32 v[84:85], v[96:97], v[46:47] op_sel_hi:[1,0]
	v_pk_mul_f32 v[86:87], v[98:99], v[46:47] op_sel_hi:[1,0]
	v_pk_mul_f32 v[84:85], v[12:13], v[84:85]
	v_pk_mul_f32 v[86:87], v[14:15], v[86:87]
	v_cvt_pk_bf16_f32 v84, v84, v85
	v_cvt_pk_bf16_f32 v85, v86, v87
	global_store_dwordx2 v[64:65], v[84:85], off offset:1536
	s_waitcnt vmcnt(31)
	v_mov_b32_e32 v46, v101
	s_waitcnt vmcnt(30)
	v_mov_b32_e32 v47, v105
	v_mov_b32_e32 v42, v100
	v_mov_b32_e32 v43, v104
	v_pk_mul_f32 v[46:47], v[46:47], v[46:47]
	v_mov_b32_e32 v36, v102
	v_mov_b32_e32 v37, v106
	v_pk_fma_f32 v[42:43], v[42:43], v[42:43], v[46:47]
	v_mov_b32_e32 v38, v103
	v_mov_b32_e32 v39, v107
	v_pk_fma_f32 v[36:37], v[36:37], v[36:37], v[42:43]
	s_nop 0
	v_pk_fma_f32 v[46:47], v[38:39], v[38:39], v[36:37]
	v_add_f32_e32 v17, v46, v47
	s_waitcnt vmcnt(29)
	v_mov_b32_e32 v54, v109
	s_waitcnt vmcnt(28)
	v_mov_b32_e32 v55, v113
	v_mov_b32_e32 v52, v108
	v_mov_b32_e32 v53, v112
	v_pk_mul_f32 v[54:55], v[54:55], v[54:55]
	v_mov_b32_e32 v48, v110
	v_mov_b32_e32 v49, v114
	v_pk_fma_f32 v[52:53], v[52:53], v[52:53], v[54:55]
	v_mov_b32_e32 v50, v111
	v_mov_b32_e32 v51, v115
	v_pk_fma_f32 v[48:49], v[48:49], v[48:49], v[52:53]
	s_nop 0
	v_pk_fma_f32 v[48:49], v[50:51], v[50:51], v[48:49]
	s_nop 0
	v_add_f32_e32 v17, v17, v48
	v_add_f32_e32 v17, v17, v49
	ds_bpermute_b32 v46, v22, v17
	s_waitcnt lgkmcnt(0)
	v_add_f32_e32 v17, v17, v46
	ds_bpermute_b32 v46, v23, v17
	s_waitcnt lgkmcnt(0)
	v_add_f32_e32 v17, v17, v46
	ds_bpermute_b32 v46, v24, v17
	s_waitcnt lgkmcnt(0)
	v_add_f32_e32 v17, v17, v46
	ds_bpermute_b32 v46, v25, v17
	s_waitcnt lgkmcnt(0)
	v_add_f32_e32 v17, v17, v46
	ds_bpermute_b32 v46, v26, v17
	s_waitcnt lgkmcnt(0)
	v_add_f32_e32 v17, v17, v46
	ds_bpermute_b32 v46, v27, v17
	s_waitcnt lgkmcnt(0)
	v_add_f32_e32 v17, v17, v46
	v_fmamk_f32 v17, v17, 0x3a800000, v187
	v_cmp_gt_f32_e32 vcc, s79, v17
	v_mul_f32_e32 v46, 0x4b800000, v17
	s_nop 0
	v_cndmask_b32_e32 v17, v17, v46, vcc
	v_rsq_f32_e32 v17, v17
	s_nop 0
	v_mul_f32_e32 v46, 0x45800000, v17
	v_cndmask_b32_e32 v46, v17, v46, vcc
	v_pk_mul_f32 v[100:101], v[100:101], v[46:47] op_sel_hi:[1,0]
	v_pk_mul_f32 v[102:103], v[102:103], v[46:47] op_sel_hi:[1,0]
	v_pk_mul_f32 v[100:101], v[0:1], v[100:101]
	v_pk_mul_f32 v[102:103], v[2:3], v[102:103]
	v_cvt_pk_bf16_f32 v100, v100, v101
	v_cvt_pk_bf16_f32 v101, v102, v103
	global_store_dwordx2 v[66:67], v[100:101], off
	v_pk_mul_f32 v[100:101], v[104:105], v[46:47] op_sel_hi:[1,0]
	v_pk_mul_f32 v[102:103], v[106:107], v[46:47] op_sel_hi:[1,0]
	v_pk_mul_f32 v[100:101], v[4:5], v[100:101]
	v_pk_mul_f32 v[102:103], v[6:7], v[102:103]
	v_cvt_pk_bf16_f32 v100, v100, v101
	v_cvt_pk_bf16_f32 v101, v102, v103
	global_store_dwordx2 v[66:67], v[100:101], off offset:512
	v_pk_mul_f32 v[100:101], v[108:109], v[46:47] op_sel_hi:[1,0]
	v_pk_mul_f32 v[102:103], v[110:111], v[46:47] op_sel_hi:[1,0]
	v_pk_mul_f32 v[100:101], v[8:9], v[100:101]
	v_pk_mul_f32 v[102:103], v[10:11], v[102:103]
	v_cvt_pk_bf16_f32 v100, v100, v101
	v_cvt_pk_bf16_f32 v101, v102, v103
	global_store_dwordx2 v[66:67], v[100:101], off offset:1024
	v_pk_mul_f32 v[100:101], v[112:113], v[46:47] op_sel_hi:[1,0]
	v_pk_mul_f32 v[102:103], v[114:115], v[46:47] op_sel_hi:[1,0]
	v_pk_mul_f32 v[100:101], v[12:13], v[100:101]
	v_pk_mul_f32 v[102:103], v[14:15], v[102:103]
	v_cvt_pk_bf16_f32 v100, v100, v101
	v_cvt_pk_bf16_f32 v101, v102, v103
	global_store_dwordx2 v[66:67], v[100:101], off offset:1536
	s_waitcnt vmcnt(31)
	v_mov_b32_e32 v46, v117
	s_waitcnt vmcnt(30)
	v_mov_b32_e32 v47, v121
	v_mov_b32_e32 v42, v116
	v_mov_b32_e32 v43, v120
	v_pk_mul_f32 v[46:47], v[46:47], v[46:47]
	v_mov_b32_e32 v36, v118
	v_mov_b32_e32 v37, v122
	v_pk_fma_f32 v[42:43], v[42:43], v[42:43], v[46:47]
	v_mov_b32_e32 v38, v119
	v_mov_b32_e32 v39, v123
	v_pk_fma_f32 v[36:37], v[36:37], v[36:37], v[42:43]
	s_nop 0
	v_pk_fma_f32 v[46:47], v[38:39], v[38:39], v[36:37]
	v_add_f32_e32 v17, v46, v47
	s_waitcnt vmcnt(29)
	v_mov_b32_e32 v54, v125
	s_waitcnt vmcnt(28)
	v_mov_b32_e32 v55, v129
	v_mov_b32_e32 v52, v124
	v_mov_b32_e32 v53, v128
	v_pk_mul_f32 v[54:55], v[54:55], v[54:55]
	v_mov_b32_e32 v48, v126
	v_mov_b32_e32 v49, v130
	v_pk_fma_f32 v[52:53], v[52:53], v[52:53], v[54:55]
	v_mov_b32_e32 v50, v127
	v_mov_b32_e32 v51, v131
	v_pk_fma_f32 v[48:49], v[48:49], v[48:49], v[52:53]
	s_nop 0
	v_pk_fma_f32 v[48:49], v[50:51], v[50:51], v[48:49]
	s_nop 0
	v_add_f32_e32 v17, v17, v48
	v_add_f32_e32 v17, v17, v49
	ds_bpermute_b32 v46, v22, v17
	s_waitcnt lgkmcnt(0)
	v_add_f32_e32 v17, v17, v46
	ds_bpermute_b32 v46, v23, v17
	s_waitcnt lgkmcnt(0)
	v_add_f32_e32 v17, v17, v46
	ds_bpermute_b32 v46, v24, v17
	s_waitcnt lgkmcnt(0)
	v_add_f32_e32 v17, v17, v46
	ds_bpermute_b32 v46, v25, v17
	s_waitcnt lgkmcnt(0)
	v_add_f32_e32 v17, v17, v46
	ds_bpermute_b32 v46, v26, v17
	s_waitcnt lgkmcnt(0)
	v_add_f32_e32 v17, v17, v46
	ds_bpermute_b32 v46, v27, v17
	s_waitcnt lgkmcnt(0)
	v_add_f32_e32 v17, v17, v46
	v_fmamk_f32 v17, v17, 0x3a800000, v187
	v_cmp_gt_f32_e32 vcc, s79, v17
	v_mul_f32_e32 v46, 0x4b800000, v17
	s_nop 0
	v_cndmask_b32_e32 v17, v17, v46, vcc
	v_rsq_f32_e32 v17, v17
	s_nop 0
	v_mul_f32_e32 v46, 0x45800000, v17
	v_cndmask_b32_e32 v46, v17, v46, vcc
	v_pk_mul_f32 v[116:117], v[116:117], v[46:47] op_sel_hi:[1,0]
	v_pk_mul_f32 v[118:119], v[118:119], v[46:47] op_sel_hi:[1,0]
	v_pk_mul_f32 v[116:117], v[0:1], v[116:117]
	v_pk_mul_f32 v[118:119], v[2:3], v[118:119]
	v_cvt_pk_bf16_f32 v116, v116, v117
	v_cvt_pk_bf16_f32 v117, v118, v119
	global_store_dwordx2 v[68:69], v[116:117], off
	v_pk_mul_f32 v[116:117], v[120:121], v[46:47] op_sel_hi:[1,0]
	v_pk_mul_f32 v[118:119], v[122:123], v[46:47] op_sel_hi:[1,0]
	v_pk_mul_f32 v[116:117], v[4:5], v[116:117]
	v_pk_mul_f32 v[118:119], v[6:7], v[118:119]
	v_cvt_pk_bf16_f32 v116, v116, v117
	v_cvt_pk_bf16_f32 v117, v118, v119
	global_store_dwordx2 v[68:69], v[116:117], off offset:512
	v_pk_mul_f32 v[116:117], v[124:125], v[46:47] op_sel_hi:[1,0]
	v_pk_mul_f32 v[118:119], v[126:127], v[46:47] op_sel_hi:[1,0]
	v_pk_mul_f32 v[116:117], v[8:9], v[116:117]
	v_pk_mul_f32 v[118:119], v[10:11], v[118:119]
	v_cvt_pk_bf16_f32 v116, v116, v117
	v_cvt_pk_bf16_f32 v117, v118, v119
	global_store_dwordx2 v[68:69], v[116:117], off offset:1024
	v_pk_mul_f32 v[116:117], v[128:129], v[46:47] op_sel_hi:[1,0]
	v_pk_mul_f32 v[118:119], v[130:131], v[46:47] op_sel_hi:[1,0]
	v_pk_mul_f32 v[116:117], v[12:13], v[116:117]
	v_pk_mul_f32 v[118:119], v[14:15], v[118:119]
	v_cvt_pk_bf16_f32 v116, v116, v117
	v_cvt_pk_bf16_f32 v117, v118, v119
	global_store_dwordx2 v[68:69], v[116:117], off offset:1536
	s_waitcnt vmcnt(31)
	v_mov_b32_e32 v46, v133
	s_waitcnt vmcnt(30)
	v_mov_b32_e32 v47, v137
	v_mov_b32_e32 v42, v132
	v_mov_b32_e32 v43, v136
	v_pk_mul_f32 v[46:47], v[46:47], v[46:47]
	v_mov_b32_e32 v36, v134
	v_mov_b32_e32 v37, v138
	v_pk_fma_f32 v[42:43], v[42:43], v[42:43], v[46:47]
	v_mov_b32_e32 v38, v135
	v_mov_b32_e32 v39, v139
	v_pk_fma_f32 v[36:37], v[36:37], v[36:37], v[42:43]
	s_nop 0
	v_pk_fma_f32 v[46:47], v[38:39], v[38:39], v[36:37]
	v_add_f32_e32 v17, v46, v47
	s_waitcnt vmcnt(29)
	v_mov_b32_e32 v54, v141
	s_waitcnt vmcnt(28)
	v_mov_b32_e32 v55, v145
	v_mov_b32_e32 v52, v140
	v_mov_b32_e32 v53, v144
	v_pk_mul_f32 v[54:55], v[54:55], v[54:55]
	v_mov_b32_e32 v48, v142
	v_mov_b32_e32 v49, v146
	v_pk_fma_f32 v[52:53], v[52:53], v[52:53], v[54:55]
	v_mov_b32_e32 v50, v143
	v_mov_b32_e32 v51, v147
	v_pk_fma_f32 v[48:49], v[48:49], v[48:49], v[52:53]
	s_nop 0
	v_pk_fma_f32 v[48:49], v[50:51], v[50:51], v[48:49]
	s_nop 0
	v_add_f32_e32 v17, v17, v48
	v_add_f32_e32 v17, v17, v49
	ds_bpermute_b32 v46, v22, v17
	s_waitcnt lgkmcnt(0)
	v_add_f32_e32 v17, v17, v46
	ds_bpermute_b32 v46, v23, v17
	s_waitcnt lgkmcnt(0)
	v_add_f32_e32 v17, v17, v46
	ds_bpermute_b32 v46, v24, v17
	s_waitcnt lgkmcnt(0)
	v_add_f32_e32 v17, v17, v46
	ds_bpermute_b32 v46, v25, v17
	s_waitcnt lgkmcnt(0)
	v_add_f32_e32 v17, v17, v46
	ds_bpermute_b32 v46, v26, v17
	s_waitcnt lgkmcnt(0)
	v_add_f32_e32 v17, v17, v46
	ds_bpermute_b32 v46, v27, v17
	s_waitcnt lgkmcnt(0)
	v_add_f32_e32 v17, v17, v46
	v_fmamk_f32 v17, v17, 0x3a800000, v187
	v_cmp_gt_f32_e32 vcc, s79, v17
	v_mul_f32_e32 v46, 0x4b800000, v17
	s_nop 0
	v_cndmask_b32_e32 v17, v17, v46, vcc
	v_rsq_f32_e32 v17, v17
	s_nop 0
	v_mul_f32_e32 v46, 0x45800000, v17
	v_cndmask_b32_e32 v46, v17, v46, vcc
	v_pk_mul_f32 v[132:133], v[132:133], v[46:47] op_sel_hi:[1,0]
	v_pk_mul_f32 v[134:135], v[134:135], v[46:47] op_sel_hi:[1,0]
	v_pk_mul_f32 v[132:133], v[0:1], v[132:133]
	v_pk_mul_f32 v[134:135], v[2:3], v[134:135]
	v_cvt_pk_bf16_f32 v132, v132, v133
	v_cvt_pk_bf16_f32 v133, v134, v135
	global_store_dwordx2 v[70:71], v[132:133], off
	v_pk_mul_f32 v[132:133], v[136:137], v[46:47] op_sel_hi:[1,0]
	v_pk_mul_f32 v[134:135], v[138:139], v[46:47] op_sel_hi:[1,0]
	v_pk_mul_f32 v[132:133], v[4:5], v[132:133]
	v_pk_mul_f32 v[134:135], v[6:7], v[134:135]
	v_cvt_pk_bf16_f32 v132, v132, v133
	v_cvt_pk_bf16_f32 v133, v134, v135
	global_store_dwordx2 v[70:71], v[132:133], off offset:512
	v_pk_mul_f32 v[132:133], v[140:141], v[46:47] op_sel_hi:[1,0]
	v_pk_mul_f32 v[134:135], v[142:143], v[46:47] op_sel_hi:[1,0]
	v_pk_mul_f32 v[132:133], v[8:9], v[132:133]
	v_pk_mul_f32 v[134:135], v[10:11], v[134:135]
	v_cvt_pk_bf16_f32 v132, v132, v133
	v_cvt_pk_bf16_f32 v133, v134, v135
	global_store_dwordx2 v[70:71], v[132:133], off offset:1024
	v_pk_mul_f32 v[132:133], v[144:145], v[46:47] op_sel_hi:[1,0]
	v_pk_mul_f32 v[134:135], v[146:147], v[46:47] op_sel_hi:[1,0]
	v_pk_mul_f32 v[132:133], v[12:13], v[132:133]
	v_pk_mul_f32 v[134:135], v[14:15], v[134:135]
	v_cvt_pk_bf16_f32 v132, v132, v133
	v_cvt_pk_bf16_f32 v133, v134, v135
	global_store_dwordx2 v[70:71], v[132:133], off offset:1536
	s_waitcnt vmcnt(31)
	v_mov_b32_e32 v46, v165
	s_waitcnt vmcnt(30)
	v_mov_b32_e32 v47, v169
	v_mov_b32_e32 v42, v164
	v_mov_b32_e32 v43, v168
	v_pk_mul_f32 v[46:47], v[46:47], v[46:47]
	v_mov_b32_e32 v36, v166
	v_mov_b32_e32 v37, v170
	v_pk_fma_f32 v[42:43], v[42:43], v[42:43], v[46:47]
	v_mov_b32_e32 v38, v167
	v_mov_b32_e32 v39, v171
	v_pk_fma_f32 v[36:37], v[36:37], v[36:37], v[42:43]
	s_nop 0
	v_pk_fma_f32 v[46:47], v[38:39], v[38:39], v[36:37]
	v_add_f32_e32 v17, v46, v47
	s_waitcnt vmcnt(29)
	v_mov_b32_e32 v54, v173
	s_waitcnt vmcnt(28)
	v_mov_b32_e32 v55, v177
	v_mov_b32_e32 v52, v172
	v_mov_b32_e32 v53, v176
	v_pk_mul_f32 v[54:55], v[54:55], v[54:55]
	v_mov_b32_e32 v48, v174
	v_mov_b32_e32 v49, v178
	v_pk_fma_f32 v[52:53], v[52:53], v[52:53], v[54:55]
	v_mov_b32_e32 v50, v175
	v_mov_b32_e32 v51, v179
	v_pk_fma_f32 v[48:49], v[48:49], v[48:49], v[52:53]
	s_nop 0
	v_pk_fma_f32 v[48:49], v[50:51], v[50:51], v[48:49]
	s_nop 0
	v_add_f32_e32 v17, v17, v48
	v_add_f32_e32 v17, v17, v49
	ds_bpermute_b32 v46, v22, v17
	s_waitcnt lgkmcnt(0)
	v_add_f32_e32 v17, v17, v46
	ds_bpermute_b32 v46, v23, v17
	s_waitcnt lgkmcnt(0)
	v_add_f32_e32 v17, v17, v46
	ds_bpermute_b32 v46, v24, v17
	s_waitcnt lgkmcnt(0)
	v_add_f32_e32 v17, v17, v46
	ds_bpermute_b32 v46, v25, v17
	s_waitcnt lgkmcnt(0)
	v_add_f32_e32 v17, v17, v46
	ds_bpermute_b32 v46, v26, v17
	s_waitcnt lgkmcnt(0)
	v_add_f32_e32 v17, v17, v46
	ds_bpermute_b32 v46, v27, v17
	s_waitcnt lgkmcnt(0)
	v_add_f32_e32 v17, v17, v46
	v_fmamk_f32 v17, v17, 0x3a800000, v187
	v_cmp_gt_f32_e32 vcc, s79, v17
	v_mul_f32_e32 v46, 0x4b800000, v17
	s_nop 0
	v_cndmask_b32_e32 v17, v17, v46, vcc
	v_rsq_f32_e32 v17, v17
	s_nop 0
	v_mul_f32_e32 v46, 0x45800000, v17
	v_cndmask_b32_e32 v46, v17, v46, vcc
	v_pk_mul_f32 v[164:165], v[164:165], v[46:47] op_sel_hi:[1,0]
	v_pk_mul_f32 v[166:167], v[166:167], v[46:47] op_sel_hi:[1,0]
	v_pk_mul_f32 v[164:165], v[0:1], v[164:165]
	v_pk_mul_f32 v[166:167], v[2:3], v[166:167]
	v_cvt_pk_bf16_f32 v164, v164, v165
	v_cvt_pk_bf16_f32 v165, v166, v167
	global_store_dwordx2 v[72:73], v[164:165], off
	v_pk_mul_f32 v[164:165], v[168:169], v[46:47] op_sel_hi:[1,0]
	v_pk_mul_f32 v[166:167], v[170:171], v[46:47] op_sel_hi:[1,0]
	v_pk_mul_f32 v[164:165], v[4:5], v[164:165]
	v_pk_mul_f32 v[166:167], v[6:7], v[166:167]
	v_cvt_pk_bf16_f32 v164, v164, v165
	v_cvt_pk_bf16_f32 v165, v166, v167
	global_store_dwordx2 v[72:73], v[164:165], off offset:512
	v_pk_mul_f32 v[164:165], v[172:173], v[46:47] op_sel_hi:[1,0]
	v_pk_mul_f32 v[166:167], v[174:175], v[46:47] op_sel_hi:[1,0]
	v_pk_mul_f32 v[164:165], v[8:9], v[164:165]
	v_pk_mul_f32 v[166:167], v[10:11], v[166:167]
	v_cvt_pk_bf16_f32 v164, v164, v165
	v_cvt_pk_bf16_f32 v165, v166, v167
	global_store_dwordx2 v[72:73], v[164:165], off offset:1024
	v_pk_mul_f32 v[164:165], v[176:177], v[46:47] op_sel_hi:[1,0]
	v_pk_mul_f32 v[166:167], v[178:179], v[46:47] op_sel_hi:[1,0]
	v_pk_mul_f32 v[164:165], v[12:13], v[164:165]
	v_pk_mul_f32 v[166:167], v[14:15], v[166:167]
	v_cvt_pk_bf16_f32 v164, v164, v165
	v_cvt_pk_bf16_f32 v165, v166, v167
	global_store_dwordx2 v[72:73], v[164:165], off offset:1536
	s_waitcnt vmcnt(31)
	v_mov_b32_e32 v46, v211
	s_waitcnt vmcnt(30)
	v_mov_b32_e32 v47, v215
	v_mov_b32_e32 v42, v210
	v_mov_b32_e32 v43, v214
	v_pk_mul_f32 v[46:47], v[46:47], v[46:47]
	v_mov_b32_e32 v36, v212
	v_mov_b32_e32 v37, v216
	v_pk_fma_f32 v[42:43], v[42:43], v[42:43], v[46:47]
	v_mov_b32_e32 v38, v213
	v_mov_b32_e32 v39, v217
	v_pk_fma_f32 v[36:37], v[36:37], v[36:37], v[42:43]
	s_nop 0
	v_pk_fma_f32 v[46:47], v[38:39], v[38:39], v[36:37]
	v_add_f32_e32 v17, v46, v47
	s_waitcnt vmcnt(29)
	v_mov_b32_e32 v54, v219
	s_waitcnt vmcnt(28)
	v_mov_b32_e32 v55, v223
	v_mov_b32_e32 v52, v218
	v_mov_b32_e32 v53, v222
	v_pk_mul_f32 v[54:55], v[54:55], v[54:55]
	v_mov_b32_e32 v48, v220
	v_mov_b32_e32 v49, v224
	v_pk_fma_f32 v[52:53], v[52:53], v[52:53], v[54:55]
	v_mov_b32_e32 v50, v221
	v_mov_b32_e32 v51, v225
	v_pk_fma_f32 v[48:49], v[48:49], v[48:49], v[52:53]
	s_nop 0
	v_pk_fma_f32 v[48:49], v[50:51], v[50:51], v[48:49]
	s_nop 0
	v_add_f32_e32 v17, v17, v48
	v_add_f32_e32 v17, v17, v49
	ds_bpermute_b32 v46, v22, v17
	s_waitcnt lgkmcnt(0)
	v_add_f32_e32 v17, v17, v46
	ds_bpermute_b32 v46, v23, v17
	s_waitcnt lgkmcnt(0)
	v_add_f32_e32 v17, v17, v46
	ds_bpermute_b32 v46, v24, v17
	s_waitcnt lgkmcnt(0)
	v_add_f32_e32 v17, v17, v46
	ds_bpermute_b32 v46, v25, v17
	s_waitcnt lgkmcnt(0)
	v_add_f32_e32 v17, v17, v46
	ds_bpermute_b32 v46, v26, v17
	s_waitcnt lgkmcnt(0)
	v_add_f32_e32 v17, v17, v46
	ds_bpermute_b32 v46, v27, v17
	s_waitcnt lgkmcnt(0)
	v_add_f32_e32 v17, v17, v46
	v_fmamk_f32 v17, v17, 0x3a800000, v187
	v_cmp_gt_f32_e32 vcc, s79, v17
	v_mul_f32_e32 v46, 0x4b800000, v17
	s_nop 0
	v_cndmask_b32_e32 v17, v17, v46, vcc
	v_rsq_f32_e32 v17, v17
	s_nop 0
	v_mul_f32_e32 v46, 0x45800000, v17
	v_cndmask_b32_e32 v46, v17, v46, vcc
	v_pk_mul_f32 v[210:211], v[210:211], v[46:47] op_sel_hi:[1,0]
	v_pk_mul_f32 v[212:213], v[212:213], v[46:47] op_sel_hi:[1,0]
	v_pk_mul_f32 v[210:211], v[0:1], v[210:211]
	v_pk_mul_f32 v[212:213], v[2:3], v[212:213]
	v_cvt_pk_bf16_f32 v210, v210, v211
	v_cvt_pk_bf16_f32 v211, v212, v213
	global_store_dwordx2 v[74:75], v[210:211], off
	v_pk_mul_f32 v[210:211], v[214:215], v[46:47] op_sel_hi:[1,0]
	v_pk_mul_f32 v[212:213], v[216:217], v[46:47] op_sel_hi:[1,0]
	v_pk_mul_f32 v[210:211], v[4:5], v[210:211]
	v_pk_mul_f32 v[212:213], v[6:7], v[212:213]
	v_cvt_pk_bf16_f32 v210, v210, v211
	v_cvt_pk_bf16_f32 v211, v212, v213
	global_store_dwordx2 v[74:75], v[210:211], off offset:512
	v_pk_mul_f32 v[210:211], v[218:219], v[46:47] op_sel_hi:[1,0]
	v_pk_mul_f32 v[212:213], v[220:221], v[46:47] op_sel_hi:[1,0]
	v_pk_mul_f32 v[210:211], v[8:9], v[210:211]
	v_pk_mul_f32 v[212:213], v[10:11], v[212:213]
	v_cvt_pk_bf16_f32 v210, v210, v211
	v_cvt_pk_bf16_f32 v211, v212, v213
	global_store_dwordx2 v[74:75], v[210:211], off offset:1024
	v_pk_mul_f32 v[210:211], v[222:223], v[46:47] op_sel_hi:[1,0]
	v_pk_mul_f32 v[212:213], v[224:225], v[46:47] op_sel_hi:[1,0]
	v_pk_mul_f32 v[210:211], v[12:13], v[210:211]
	v_pk_mul_f32 v[212:213], v[14:15], v[212:213]
	v_cvt_pk_bf16_f32 v210, v210, v211
	v_cvt_pk_bf16_f32 v211, v212, v213
	global_store_dwordx2 v[74:75], v[210:211], off offset:1536
	s_waitcnt vmcnt(31)
	v_mov_b32_e32 v46, v227
	s_waitcnt vmcnt(30)
	v_mov_b32_e32 v47, v231
	v_mov_b32_e32 v42, v226
	v_mov_b32_e32 v43, v230
	v_pk_mul_f32 v[46:47], v[46:47], v[46:47]
	v_mov_b32_e32 v36, v228
	v_mov_b32_e32 v37, v232
	v_pk_fma_f32 v[42:43], v[42:43], v[42:43], v[46:47]
	v_mov_b32_e32 v38, v229
	v_mov_b32_e32 v39, v233
	v_pk_fma_f32 v[36:37], v[36:37], v[36:37], v[42:43]
	s_nop 0
	v_pk_fma_f32 v[46:47], v[38:39], v[38:39], v[36:37]
	v_add_f32_e32 v17, v46, v47
	s_waitcnt vmcnt(29)
	v_mov_b32_e32 v54, v235
	s_waitcnt vmcnt(28)
	v_mov_b32_e32 v55, v239
	v_mov_b32_e32 v52, v234
	v_mov_b32_e32 v53, v238
	v_pk_mul_f32 v[54:55], v[54:55], v[54:55]
	v_mov_b32_e32 v48, v236
	v_mov_b32_e32 v49, v240
	v_pk_fma_f32 v[52:53], v[52:53], v[52:53], v[54:55]
	v_mov_b32_e32 v50, v237
	v_mov_b32_e32 v51, v241
	v_pk_fma_f32 v[48:49], v[48:49], v[48:49], v[52:53]
	s_nop 0
	v_pk_fma_f32 v[48:49], v[50:51], v[50:51], v[48:49]
	s_nop 0
	v_add_f32_e32 v17, v17, v48
	v_add_f32_e32 v17, v17, v49
	ds_bpermute_b32 v46, v22, v17
	s_waitcnt lgkmcnt(0)
	v_add_f32_e32 v17, v17, v46
	ds_bpermute_b32 v46, v23, v17
	s_waitcnt lgkmcnt(0)
	v_add_f32_e32 v17, v17, v46
	ds_bpermute_b32 v46, v24, v17
	s_waitcnt lgkmcnt(0)
	v_add_f32_e32 v17, v17, v46
	ds_bpermute_b32 v46, v25, v17
	s_waitcnt lgkmcnt(0)
	v_add_f32_e32 v17, v17, v46
	ds_bpermute_b32 v46, v26, v17
	s_waitcnt lgkmcnt(0)
	v_add_f32_e32 v17, v17, v46
	ds_bpermute_b32 v46, v27, v17
	s_waitcnt lgkmcnt(0)
	v_add_f32_e32 v17, v17, v46
	v_fmamk_f32 v17, v17, 0x3a800000, v187
	v_cmp_gt_f32_e32 vcc, s79, v17
	v_mul_f32_e32 v46, 0x4b800000, v17
	s_nop 0
	v_cndmask_b32_e32 v17, v17, v46, vcc
	v_rsq_f32_e32 v17, v17
	s_nop 0
	v_mul_f32_e32 v46, 0x45800000, v17
	v_cndmask_b32_e32 v46, v17, v46, vcc
	v_pk_mul_f32 v[226:227], v[226:227], v[46:47] op_sel_hi:[1,0]
	v_pk_mul_f32 v[228:229], v[228:229], v[46:47] op_sel_hi:[1,0]
	v_pk_mul_f32 v[226:227], v[0:1], v[226:227]
	v_pk_mul_f32 v[228:229], v[2:3], v[228:229]
	v_cvt_pk_bf16_f32 v226, v226, v227
	v_cvt_pk_bf16_f32 v227, v228, v229
	global_store_dwordx2 v[76:77], v[226:227], off
	v_pk_mul_f32 v[226:227], v[230:231], v[46:47] op_sel_hi:[1,0]
	v_pk_mul_f32 v[228:229], v[232:233], v[46:47] op_sel_hi:[1,0]
	v_pk_mul_f32 v[226:227], v[4:5], v[226:227]
	v_pk_mul_f32 v[228:229], v[6:7], v[228:229]
	v_cvt_pk_bf16_f32 v226, v226, v227
	v_cvt_pk_bf16_f32 v227, v228, v229
	global_store_dwordx2 v[76:77], v[226:227], off offset:512
	v_pk_mul_f32 v[226:227], v[234:235], v[46:47] op_sel_hi:[1,0]
	v_pk_mul_f32 v[228:229], v[236:237], v[46:47] op_sel_hi:[1,0]
	v_pk_mul_f32 v[226:227], v[8:9], v[226:227]
	v_pk_mul_f32 v[228:229], v[10:11], v[228:229]
	v_cvt_pk_bf16_f32 v226, v226, v227
	v_cvt_pk_bf16_f32 v227, v228, v229
	global_store_dwordx2 v[76:77], v[226:227], off offset:1024
	v_pk_mul_f32 v[226:227], v[238:239], v[46:47] op_sel_hi:[1,0]
	v_pk_mul_f32 v[228:229], v[240:241], v[46:47] op_sel_hi:[1,0]
	v_pk_mul_f32 v[226:227], v[12:13], v[226:227]
	v_pk_mul_f32 v[228:229], v[14:15], v[228:229]
	v_cvt_pk_bf16_f32 v226, v226, v227
	v_cvt_pk_bf16_f32 v227, v228, v229
	global_store_dwordx2 v[76:77], v[226:227], off offset:1536
	s_branch .LBB0_287
